# router affinity loop: 64 serialized load-drain-MFMA steps replaced by 16 unrolled trips with 4 register sets (60 loads in flight), same operation order
# speedup vs baseline: 1.2144x; 1.0200x over previous
; __device__ __forceinline__ void phase_router(const Params& p, int l, const float* xlat, const float* xctx, int nrows) {
;     ...
;   for (int tile = gw; tile < ntile; tile += nw) {
;     const int row0 = tile * 16;
;     const int cond = row_cond(row0);
;     const float* xr = (row0 < T_LAT ? xlat + (size_t)(row0 + l16) * DM : xctx + (size_t)(row0 - T_LAT + l16) * DM) + quad * 4;
;     const float* wp = p.WR2 + (size_t)(l * 3 + cond) * 16384 + quad * 64 + l16;
;     f32x4 acc = (f32x4){0.f, 0.f, 0.f, 0.f};
;     float ss = 0.f;
; #pragma unroll 4
;     for (int s = 0; s < 64; ++s) {
;       const float4 a = *(const float4*)(xr + s * 16);
;       const float b0 = wp[s * 256], b1 = wp[s * 256 + 16], b2 = wp[s * 256 + 32], b3 = wp[s * 256 + 48];
;       ss += a.x * a.x + a.y * a.y + a.z * a.z + a.w * a.w;
;       acc = __builtin_amdgcn_mfma_f32_16x16x4f32(a.x, b0, acc, 0, 0, 0);
;       acc = __builtin_amdgcn_mfma_f32_16x16x4f32(a.y, b1, acc, 0, 0, 0);
;       acc = __builtin_amdgcn_mfma_f32_16x16x4f32(a.z, b2, acc, 0, 0, 0);
;       acc = __builtin_amdgcn_mfma_f32_16x16x4f32(a.w, b3, acc, 0, 0, 0);
.LBB0_911:
	v_lshlrev_b32_e32 v29, 4, v11
	v_min_i32_e32 v0, 0x4000, v29
	s_movk_i32 s0, 0x400
	v_ashrrev_i32_e32 v12, 13, v0
	v_add_u32_e32 v0, v21, v29
	v_or_b32_e32 v6, v29, v20
	v_cmp_gt_i32_e32 vcc, s0, v11
	v_ashrrev_i32_e32 v7, 31, v6
	v_mov_b32_e32 v8, s5
	v_cndmask_b32_e32 v6, v0, v6, vcc
	v_mov_b32_e32 v0, s83
	v_cndmask_b32_e32 v7, 0, v7, vcc
	v_cndmask_b32_e32 v9, v0, v8, vcc
	v_mov_b32_e32 v0, s82
	v_mov_b32_e32 v8, s4
	s_mul_i32 s0, s36, 3
	v_cndmask_b32_e32 v8, v0, v8, vcc
	v_lshlrev_b64 v[6:7], 12, v[6:7]
	v_add_u32_e32 v12, s0, v12
	v_lshl_add_u64 v[6:7], v[8:9], 0, v[6:7]
	v_lshlrev_b32_e32 v0, 2, v10
	v_ashrrev_i32_e32 v13, 31, v12
	v_lshl_add_u64 v[14:15], v[6:7], 0, v[0:1]
	v_lshlrev_b64 v[6:7], 16, v[12:13]
	v_mov_b32_e32 v0, 0
	v_lshl_add_u64 v[16:17], v[2:3], 0, v[6:7]
	s_mov_b64 s[0:1], 0
	v_mov_b32_e32 v6, 0
	v_mov_b32_e32 v7, v0
	v_mov_b32_e32 v8, v0
	v_mov_b32_e32 v9, v0
	v_lshl_add_u64 v[18:19], v[14:15], 0, s[0:1]
	global_load_dword v88, v[16:17], off
	global_load_dword v89, v[16:17], off offset:64
	global_load_dword v90, v[16:17], off offset:128
	global_load_dword v91, v[16:17], off offset:192
	global_load_dwordx4 v[92:95], v[18:19], off
	global_load_dword v96, v[16:17], off offset:1024
	global_load_dword v97, v[16:17], off offset:1088
	global_load_dword v98, v[16:17], off offset:1152
	global_load_dword v99, v[16:17], off offset:1216
	global_load_dwordx4 v[100:103], v[18:19], off offset:64
	global_load_dword v104, v[16:17], off offset:2048
	global_load_dword v105, v[16:17], off offset:2112
	global_load_dword v106, v[16:17], off offset:2176
	global_load_dword v107, v[16:17], off offset:2240
	global_load_dwordx4 v[108:111], v[18:19], off offset:128
	global_load_dword v112, v[16:17], off offset:3072
	global_load_dword v113, v[16:17], off offset:3136
	global_load_dword v114, v[16:17], off offset:3200
	global_load_dword v115, v[16:17], off offset:3264
	global_load_dwordx4 v[116:119], v[18:19], off offset:192
	v_lshl_add_u64 v[16:17], v[16:17], 0, s[92:93]
	s_add_u32 s0, s0, 0x100
	s_addc_u32 s1, s1, 0
	v_lshl_add_u64 v[18:19], v[14:15], 0, s[0:1]
	global_load_dword v120, v[16:17], off
	global_load_dword v121, v[16:17], off offset:64
	global_load_dword v122, v[16:17], off offset:128
	global_load_dword v123, v[16:17], off offset:192
	global_load_dwordx4 v[124:127], v[18:19], off
	global_load_dword v128, v[16:17], off offset:1024
	global_load_dword v129, v[16:17], off offset:1088
	global_load_dword v130, v[16:17], off offset:1152
	global_load_dword v131, v[16:17], off offset:1216
	global_load_dwordx4 v[132:135], v[18:19], off offset:64
	global_load_dword v136, v[16:17], off offset:2048
	global_load_dword v137, v[16:17], off offset:2112
	global_load_dword v138, v[16:17], off offset:2176
	global_load_dword v139, v[16:17], off offset:2240
	global_load_dwordx4 v[140:143], v[18:19], off offset:128
	global_load_dword v144, v[16:17], off offset:3072
	global_load_dword v145, v[16:17], off offset:3136
	global_load_dword v146, v[16:17], off offset:3200
	global_load_dword v147, v[16:17], off offset:3264
	global_load_dwordx4 v[148:151], v[18:19], off offset:192
	v_lshl_add_u64 v[16:17], v[16:17], 0, s[92:93]
	s_add_u32 s0, s0, 0x100
	s_addc_u32 s1, s1, 0
	v_lshl_add_u64 v[18:19], v[14:15], 0, s[0:1]
	global_load_dword v152, v[16:17], off
	global_load_dword v153, v[16:17], off offset:64
	global_load_dword v154, v[16:17], off offset:128
	global_load_dword v155, v[16:17], off offset:192
	global_load_dwordx4 v[156:159], v[18:19], off
	global_load_dword v160, v[16:17], off offset:1024
	global_load_dword v161, v[16:17], off offset:1088
	global_load_dword v162, v[16:17], off offset:1152
	global_load_dword v163, v[16:17], off offset:1216
	global_load_dwordx4 v[164:167], v[18:19], off offset:64
	global_load_dword v168, v[16:17], off offset:2048
	global_load_dword v169, v[16:17], off offset:2112
	global_load_dword v170, v[16:17], off offset:2176
	global_load_dword v171, v[16:17], off offset:2240
	global_load_dwordx4 v[172:175], v[18:19], off offset:128
	global_load_dword v176, v[16:17], off offset:3072
	global_load_dword v177, v[16:17], off offset:3136
	global_load_dword v178, v[16:17], off offset:3200
	global_load_dword v179, v[16:17], off offset:3264
	global_load_dwordx4 v[180:183], v[18:19], off offset:192
	v_lshl_add_u64 v[16:17], v[16:17], 0, s[92:93]
	s_add_u32 s0, s0, 0x100
	s_addc_u32 s1, s1, 0
	v_lshl_add_u64 v[18:19], v[14:15], 0, s[0:1]
	global_load_dword v38, v[16:17], off
	global_load_dword v39, v[16:17], off offset:64
	global_load_dword v40, v[16:17], off offset:128
	global_load_dword v41, v[16:17], off offset:192
	global_load_dwordx4 v[42:45], v[18:19], off
	global_load_dword v54, v[16:17], off offset:1024
	global_load_dword v55, v[16:17], off offset:1088
	global_load_dword v56, v[16:17], off offset:1152
	global_load_dword v57, v[16:17], off offset:1216
	global_load_dwordx4 v[58:61], v[18:19], off offset:64
	global_load_dword v62, v[16:17], off offset:2048
	global_load_dword v63, v[16:17], off offset:2112
	global_load_dword v64, v[16:17], off offset:2176
	global_load_dword v65, v[16:17], off offset:2240
	global_load_dwordx4 v[66:69], v[18:19], off offset:128
	global_load_dword v70, v[16:17], off offset:3072
	global_load_dword v71, v[16:17], off offset:3136
	global_load_dword v72, v[16:17], off offset:3200
	global_load_dword v73, v[16:17], off offset:3264
	global_load_dwordx4 v[74:77], v[18:19], off offset:192
	v_lshl_add_u64 v[16:17], v[16:17], 0, s[92:93]
	s_add_u32 s0, s0, 0x100
	s_addc_u32 s1, s1, 0
	v_lshl_add_u64 v[18:19], v[14:15], 0, s[0:1]
	s_waitcnt vmcnt(60)
; __device__ __forceinline__ void phase_router(const Params& p, int l, const float* xlat, const float* xctx, int nrows) {
;     ...
;     for (int s = 0; s < 64; ++s) {
;       const float4 a = *(const float4*)(xr + s * 16);
;       const float b0 = wp[s * 256], b1 = wp[s * 256 + 16], b2 = wp[s * 256 + 32], b3 = wp[s * 256 + 48];
;       ss += a.x * a.x + a.y * a.y + a.z * a.z + a.w * a.w;
;       acc = __builtin_amdgcn_mfma_f32_16x16x4f32(a.x, b0, acc, 0, 0, 0);
;       acc = __builtin_amdgcn_mfma_f32_16x16x4f32(a.y, b1, acc, 0, 0, 0);
;       acc = __builtin_amdgcn_mfma_f32_16x16x4f32(a.z, b2, acc, 0, 0, 0);
;       acc = __builtin_amdgcn_mfma_f32_16x16x4f32(a.w, b3, acc, 0, 0, 0);
;     }
	v_mfma_f32_16x16x4_f32 v[6:9], v92, v88, v[6:9]
	v_mul_f32_e64 v34, v92, v92
	v_mul_f32_e64 v35, v93, v93
	v_mul_f32_e64 v36, v94, v94
	v_mul_f32_e64 v37, v95, v95
	v_add_f32_e32 v34, v34, v35
	v_add_f32_e32 v34, v34, v36
	v_add_f32_e32 v34, v34, v37
	v_add_f32_e32 v0, v0, v34
	v_mfma_f32_16x16x4_f32 v[6:9], v93, v89, v[6:9]
	v_mfma_f32_16x16x4_f32 v[6:9], v94, v90, v[6:9]
	v_mfma_f32_16x16x4_f32 v[6:9], v95, v91, v[6:9]
	v_mfma_f32_16x16x4_f32 v[6:9], v100, v96, v[6:9]
	v_mul_f32_e64 v34, v100, v100
	v_mul_f32_e64 v35, v101, v101
	v_mul_f32_e64 v36, v102, v102
	v_mul_f32_e64 v37, v103, v103
	v_add_f32_e32 v34, v34, v35
	v_add_f32_e32 v34, v34, v36
	v_add_f32_e32 v34, v34, v37
	v_add_f32_e32 v0, v0, v34
	v_mfma_f32_16x16x4_f32 v[6:9], v101, v97, v[6:9]
	v_mfma_f32_16x16x4_f32 v[6:9], v102, v98, v[6:9]
	v_mfma_f32_16x16x4_f32 v[6:9], v103, v99, v[6:9]
	v_mfma_f32_16x16x4_f32 v[6:9], v108, v104, v[6:9]
	v_mul_f32_e64 v34, v108, v108
	v_mul_f32_e64 v35, v109, v109
	v_mul_f32_e64 v36, v110, v110
	v_mul_f32_e64 v37, v111, v111
	v_add_f32_e32 v34, v34, v35
	v_add_f32_e32 v34, v34, v36
	v_add_f32_e32 v34, v34, v37
	v_add_f32_e32 v0, v0, v34
	v_mfma_f32_16x16x4_f32 v[6:9], v109, v105, v[6:9]
	v_mfma_f32_16x16x4_f32 v[6:9], v110, v106, v[6:9]
	v_mfma_f32_16x16x4_f32 v[6:9], v111, v107, v[6:9]
	v_mfma_f32_16x16x4_f32 v[6:9], v116, v112, v[6:9]
	v_mul_f32_e64 v34, v116, v116
	v_mul_f32_e64 v35, v117, v117
	v_mul_f32_e64 v36, v118, v118
	v_mul_f32_e64 v37, v119, v119
	v_add_f32_e32 v34, v34, v35
	v_add_f32_e32 v34, v34, v36
	v_add_f32_e32 v34, v34, v37
	v_add_f32_e32 v0, v0, v34
	v_mfma_f32_16x16x4_f32 v[6:9], v117, v113, v[6:9]
	v_mfma_f32_16x16x4_f32 v[6:9], v118, v114, v[6:9]
	v_mfma_f32_16x16x4_f32 v[6:9], v119, v115, v[6:9]
	global_load_dword v88, v[16:17], off
	global_load_dword v89, v[16:17], off offset:64
	global_load_dword v90, v[16:17], off offset:128
	global_load_dword v91, v[16:17], off offset:192
	global_load_dwordx4 v[92:95], v[18:19], off
	global_load_dword v96, v[16:17], off offset:1024
	global_load_dword v97, v[16:17], off offset:1088
	global_load_dword v98, v[16:17], off offset:1152
	global_load_dword v99, v[16:17], off offset:1216
	global_load_dwordx4 v[100:103], v[18:19], off offset:64
	global_load_dword v104, v[16:17], off offset:2048
	global_load_dword v105, v[16:17], off offset:2112
	global_load_dword v106, v[16:17], off offset:2176
	global_load_dword v107, v[16:17], off offset:2240
	global_load_dwordx4 v[108:111], v[18:19], off offset:128
	global_load_dword v112, v[16:17], off offset:3072
	global_load_dword v113, v[16:17], off offset:3136
	global_load_dword v114, v[16:17], off offset:3200
	global_load_dword v115, v[16:17], off offset:3264
	global_load_dwordx4 v[116:119], v[18:19], off offset:192
	v_lshl_add_u64 v[16:17], v[16:17], 0, s[92:93]
	s_add_u32 s0, s0, 0x100
	s_addc_u32 s1, s1, 0
	v_lshl_add_u64 v[18:19], v[14:15], 0, s[0:1]
	s_waitcnt vmcnt(60)
	v_mfma_f32_16x16x4_f32 v[6:9], v124, v120, v[6:9]
	v_mul_f32_e64 v34, v124, v124
	v_mul_f32_e64 v35, v125, v125
	v_mul_f32_e64 v36, v126, v126
	v_mul_f32_e64 v37, v127, v127
	v_add_f32_e32 v34, v34, v35
	v_add_f32_e32 v34, v34, v36
	v_add_f32_e32 v34, v34, v37
	v_add_f32_e32 v0, v0, v34
	v_mfma_f32_16x16x4_f32 v[6:9], v125, v121, v[6:9]
	v_mfma_f32_16x16x4_f32 v[6:9], v126, v122, v[6:9]
	v_mfma_f32_16x16x4_f32 v[6:9], v127, v123, v[6:9]
	v_mfma_f32_16x16x4_f32 v[6:9], v132, v128, v[6:9]
	v_mul_f32_e64 v34, v132, v132
	v_mul_f32_e64 v35, v133, v133
	v_mul_f32_e64 v36, v134, v134
	v_mul_f32_e64 v37, v135, v135
	v_add_f32_e32 v34, v34, v35
	v_add_f32_e32 v34, v34, v36
	v_add_f32_e32 v34, v34, v37
	v_add_f32_e32 v0, v0, v34
	v_mfma_f32_16x16x4_f32 v[6:9], v133, v129, v[6:9]
	v_mfma_f32_16x16x4_f32 v[6:9], v134, v130, v[6:9]
	v_mfma_f32_16x16x4_f32 v[6:9], v135, v131, v[6:9]
	v_mfma_f32_16x16x4_f32 v[6:9], v140, v136, v[6:9]
	v_mul_f32_e64 v34, v140, v140
	v_mul_f32_e64 v35, v141, v141
	v_mul_f32_e64 v36, v142, v142
	v_mul_f32_e64 v37, v143, v143
	v_add_f32_e32 v34, v34, v35
	v_add_f32_e32 v34, v34, v36
	v_add_f32_e32 v34, v34, v37
	v_add_f32_e32 v0, v0, v34
	v_mfma_f32_16x16x4_f32 v[6:9], v141, v137, v[6:9]
	v_mfma_f32_16x16x4_f32 v[6:9], v142, v138, v[6:9]
	v_mfma_f32_16x16x4_f32 v[6:9], v143, v139, v[6:9]
	v_mfma_f32_16x16x4_f32 v[6:9], v148, v144, v[6:9]
	v_mul_f32_e64 v34, v148, v148
	v_mul_f32_e64 v35, v149, v149
	v_mul_f32_e64 v36, v150, v150
	v_mul_f32_e64 v37, v151, v151
	v_add_f32_e32 v34, v34, v35
	v_add_f32_e32 v34, v34, v36
	v_add_f32_e32 v34, v34, v37
	v_add_f32_e32 v0, v0, v34
	v_mfma_f32_16x16x4_f32 v[6:9], v149, v145, v[6:9]
	v_mfma_f32_16x16x4_f32 v[6:9], v150, v146, v[6:9]
	v_mfma_f32_16x16x4_f32 v[6:9], v151, v147, v[6:9]
	global_load_dword v120, v[16:17], off
	global_load_dword v121, v[16:17], off offset:64
	global_load_dword v122, v[16:17], off offset:128
	global_load_dword v123, v[16:17], off offset:192
	global_load_dwordx4 v[124:127], v[18:19], off
	global_load_dword v128, v[16:17], off offset:1024
	global_load_dword v129, v[16:17], off offset:1088
	global_load_dword v130, v[16:17], off offset:1152
	global_load_dword v131, v[16:17], off offset:1216
	global_load_dwordx4 v[132:135], v[18:19], off offset:64
	global_load_dword v136, v[16:17], off offset:2048
	global_load_dword v137, v[16:17], off offset:2112
	global_load_dword v138, v[16:17], off offset:2176
	global_load_dword v139, v[16:17], off offset:2240
	global_load_dwordx4 v[140:143], v[18:19], off offset:128
	global_load_dword v144, v[16:17], off offset:3072
	global_load_dword v145, v[16:17], off offset:3136
	global_load_dword v146, v[16:17], off offset:3200
	global_load_dword v147, v[16:17], off offset:3264
	global_load_dwordx4 v[148:151], v[18:19], off offset:192
	v_lshl_add_u64 v[16:17], v[16:17], 0, s[92:93]
	s_add_u32 s0, s0, 0x100
	s_addc_u32 s1, s1, 0
	v_lshl_add_u64 v[18:19], v[14:15], 0, s[0:1]
	s_waitcnt vmcnt(60)
; __device__ __forceinline__ void phase_router(const Params& p, int l, const float* xlat, const float* xctx, int nrows) {
;     ...
;     for (int s = 0; s < 64; ++s) {
;       const float4 a = *(const float4*)(xr + s * 16);
;       const float b0 = wp[s * 256], b1 = wp[s * 256 + 16], b2 = wp[s * 256 + 32], b3 = wp[s * 256 + 48];
;       ss += a.x * a.x + a.y * a.y + a.z * a.z + a.w * a.w;
;       acc = __builtin_amdgcn_mfma_f32_16x16x4f32(a.x, b0, acc, 0, 0, 0);
;       acc = __builtin_amdgcn_mfma_f32_16x16x4f32(a.y, b1, acc, 0, 0, 0);
;       acc = __builtin_amdgcn_mfma_f32_16x16x4f32(a.z, b2, acc, 0, 0, 0);
;       acc = __builtin_amdgcn_mfma_f32_16x16x4f32(a.w, b3, acc, 0, 0, 0);
;     }
	v_mfma_f32_16x16x4_f32 v[6:9], v156, v152, v[6:9]
	v_mul_f32_e64 v34, v156, v156
	v_mul_f32_e64 v35, v157, v157
	v_mul_f32_e64 v36, v158, v158
	v_mul_f32_e64 v37, v159, v159
	v_add_f32_e32 v34, v34, v35
	v_add_f32_e32 v34, v34, v36
	v_add_f32_e32 v34, v34, v37
	v_add_f32_e32 v0, v0, v34
	v_mfma_f32_16x16x4_f32 v[6:9], v157, v153, v[6:9]
	v_mfma_f32_16x16x4_f32 v[6:9], v158, v154, v[6:9]
	v_mfma_f32_16x16x4_f32 v[6:9], v159, v155, v[6:9]
	v_mfma_f32_16x16x4_f32 v[6:9], v164, v160, v[6:9]
	v_mul_f32_e64 v34, v164, v164
	v_mul_f32_e64 v35, v165, v165
	v_mul_f32_e64 v36, v166, v166
	v_mul_f32_e64 v37, v167, v167
	v_add_f32_e32 v34, v34, v35
	v_add_f32_e32 v34, v34, v36
	v_add_f32_e32 v34, v34, v37
	v_add_f32_e32 v0, v0, v34
	v_mfma_f32_16x16x4_f32 v[6:9], v165, v161, v[6:9]
	v_mfma_f32_16x16x4_f32 v[6:9], v166, v162, v[6:9]
	v_mfma_f32_16x16x4_f32 v[6:9], v167, v163, v[6:9]
	v_mfma_f32_16x16x4_f32 v[6:9], v172, v168, v[6:9]
	v_mul_f32_e64 v34, v172, v172
	v_mul_f32_e64 v35, v173, v173
	v_mul_f32_e64 v36, v174, v174
	v_mul_f32_e64 v37, v175, v175
	v_add_f32_e32 v34, v34, v35
	v_add_f32_e32 v34, v34, v36
	v_add_f32_e32 v34, v34, v37
	v_add_f32_e32 v0, v0, v34
	v_mfma_f32_16x16x4_f32 v[6:9], v173, v169, v[6:9]
	v_mfma_f32_16x16x4_f32 v[6:9], v174, v170, v[6:9]
	v_mfma_f32_16x16x4_f32 v[6:9], v175, v171, v[6:9]
	v_mfma_f32_16x16x4_f32 v[6:9], v180, v176, v[6:9]
	v_mul_f32_e64 v34, v180, v180
	v_mul_f32_e64 v35, v181, v181
	v_mul_f32_e64 v36, v182, v182
	v_mul_f32_e64 v37, v183, v183
	v_add_f32_e32 v34, v34, v35
	v_add_f32_e32 v34, v34, v36
	v_add_f32_e32 v34, v34, v37
	v_add_f32_e32 v0, v0, v34
	v_mfma_f32_16x16x4_f32 v[6:9], v181, v177, v[6:9]
	v_mfma_f32_16x16x4_f32 v[6:9], v182, v178, v[6:9]
	v_mfma_f32_16x16x4_f32 v[6:9], v183, v179, v[6:9]
	global_load_dword v152, v[16:17], off
	global_load_dword v153, v[16:17], off offset:64
	global_load_dword v154, v[16:17], off offset:128
	global_load_dword v155, v[16:17], off offset:192
	global_load_dwordx4 v[156:159], v[18:19], off
	global_load_dword v160, v[16:17], off offset:1024
	global_load_dword v161, v[16:17], off offset:1088
	global_load_dword v162, v[16:17], off offset:1152
	global_load_dword v163, v[16:17], off offset:1216
	global_load_dwordx4 v[164:167], v[18:19], off offset:64
	global_load_dword v168, v[16:17], off offset:2048
	global_load_dword v169, v[16:17], off offset:2112
	global_load_dword v170, v[16:17], off offset:2176
	global_load_dword v171, v[16:17], off offset:2240
	global_load_dwordx4 v[172:175], v[18:19], off offset:128
	global_load_dword v176, v[16:17], off offset:3072
	global_load_dword v177, v[16:17], off offset:3136
	global_load_dword v178, v[16:17], off offset:3200
	global_load_dword v179, v[16:17], off offset:3264
	global_load_dwordx4 v[180:183], v[18:19], off offset:192
	v_lshl_add_u64 v[16:17], v[16:17], 0, s[92:93]
	s_add_u32 s0, s0, 0x100
	s_addc_u32 s1, s1, 0
	v_lshl_add_u64 v[18:19], v[14:15], 0, s[0:1]
	s_waitcnt vmcnt(60)
	v_mfma_f32_16x16x4_f32 v[6:9], v42, v38, v[6:9]
	v_mul_f32_e64 v34, v42, v42
	v_mul_f32_e64 v35, v43, v43
	v_mul_f32_e64 v36, v44, v44
	v_mul_f32_e64 v37, v45, v45
	v_add_f32_e32 v34, v34, v35
	v_add_f32_e32 v34, v34, v36
	v_add_f32_e32 v34, v34, v37
	v_add_f32_e32 v0, v0, v34
	v_mfma_f32_16x16x4_f32 v[6:9], v43, v39, v[6:9]
	v_mfma_f32_16x16x4_f32 v[6:9], v44, v40, v[6:9]
	v_mfma_f32_16x16x4_f32 v[6:9], v45, v41, v[6:9]
	v_mfma_f32_16x16x4_f32 v[6:9], v58, v54, v[6:9]
	v_mul_f32_e64 v34, v58, v58
	v_mul_f32_e64 v35, v59, v59
	v_mul_f32_e64 v36, v60, v60
	v_mul_f32_e64 v37, v61, v61
	v_add_f32_e32 v34, v34, v35
	v_add_f32_e32 v34, v34, v36
	v_add_f32_e32 v34, v34, v37
	v_add_f32_e32 v0, v0, v34
	v_mfma_f32_16x16x4_f32 v[6:9], v59, v55, v[6:9]
	v_mfma_f32_16x16x4_f32 v[6:9], v60, v56, v[6:9]
	v_mfma_f32_16x16x4_f32 v[6:9], v61, v57, v[6:9]
	v_mfma_f32_16x16x4_f32 v[6:9], v66, v62, v[6:9]
	v_mul_f32_e64 v34, v66, v66
	v_mul_f32_e64 v35, v67, v67
	v_mul_f32_e64 v36, v68, v68
	v_mul_f32_e64 v37, v69, v69
	v_add_f32_e32 v34, v34, v35
	v_add_f32_e32 v34, v34, v36
	v_add_f32_e32 v34, v34, v37
	v_add_f32_e32 v0, v0, v34
	v_mfma_f32_16x16x4_f32 v[6:9], v67, v63, v[6:9]
	v_mfma_f32_16x16x4_f32 v[6:9], v68, v64, v[6:9]
	v_mfma_f32_16x16x4_f32 v[6:9], v69, v65, v[6:9]
	v_mfma_f32_16x16x4_f32 v[6:9], v74, v70, v[6:9]
	v_mul_f32_e64 v34, v74, v74
	v_mul_f32_e64 v35, v75, v75
	v_mul_f32_e64 v36, v76, v76
	v_mul_f32_e64 v37, v77, v77
	v_add_f32_e32 v34, v34, v35
	v_add_f32_e32 v34, v34, v36
	v_add_f32_e32 v34, v34, v37
	v_add_f32_e32 v0, v0, v34
	v_mfma_f32_16x16x4_f32 v[6:9], v75, v71, v[6:9]
	v_mfma_f32_16x16x4_f32 v[6:9], v76, v72, v[6:9]
	v_mfma_f32_16x16x4_f32 v[6:9], v77, v73, v[6:9]
	global_load_dword v38, v[16:17], off
	global_load_dword v39, v[16:17], off offset:64
	global_load_dword v40, v[16:17], off offset:128
	global_load_dword v41, v[16:17], off offset:192
	global_load_dwordx4 v[42:45], v[18:19], off
	global_load_dword v54, v[16:17], off offset:1024
	global_load_dword v55, v[16:17], off offset:1088
	global_load_dword v56, v[16:17], off offset:1152
	global_load_dword v57, v[16:17], off offset:1216
	global_load_dwordx4 v[58:61], v[18:19], off offset:64
	global_load_dword v62, v[16:17], off offset:2048
	global_load_dword v63, v[16:17], off offset:2112
	global_load_dword v64, v[16:17], off offset:2176
	global_load_dword v65, v[16:17], off offset:2240
	global_load_dwordx4 v[66:69], v[18:19], off offset:128
	global_load_dword v70, v[16:17], off offset:3072
	global_load_dword v71, v[16:17], off offset:3136
	global_load_dword v72, v[16:17], off offset:3200
	global_load_dword v73, v[16:17], off offset:3264
	global_load_dwordx4 v[74:77], v[18:19], off offset:192
	v_lshl_add_u64 v[16:17], v[16:17], 0, s[92:93]
	s_add_u32 s0, s0, 0x100
	s_addc_u32 s1, s1, 0
	v_lshl_add_u64 v[18:19], v[14:15], 0, s[0:1]
	s_waitcnt vmcnt(60)
; __device__ __forceinline__ void phase_router(const Params& p, int l, const float* xlat, const float* xctx, int nrows) {
;     ...
;     for (int s = 0; s < 64; ++s) {
;       const float4 a = *(const float4*)(xr + s * 16);
;       const float b0 = wp[s * 256], b1 = wp[s * 256 + 16], b2 = wp[s * 256 + 32], b3 = wp[s * 256 + 48];
;       ss += a.x * a.x + a.y * a.y + a.z * a.z + a.w * a.w;
;       acc = __builtin_amdgcn_mfma_f32_16x16x4f32(a.x, b0, acc, 0, 0, 0);
;       acc = __builtin_amdgcn_mfma_f32_16x16x4f32(a.y, b1, acc, 0, 0, 0);
;       acc = __builtin_amdgcn_mfma_f32_16x16x4f32(a.z, b2, acc, 0, 0, 0);
;       acc = __builtin_amdgcn_mfma_f32_16x16x4f32(a.w, b3, acc, 0, 0, 0);
;     }
	v_mfma_f32_16x16x4_f32 v[6:9], v92, v88, v[6:9]
	v_mul_f32_e64 v34, v92, v92
	v_mul_f32_e64 v35, v93, v93
	v_mul_f32_e64 v36, v94, v94
	v_mul_f32_e64 v37, v95, v95
	v_add_f32_e32 v34, v34, v35
	v_add_f32_e32 v34, v34, v36
	v_add_f32_e32 v34, v34, v37
	v_add_f32_e32 v0, v0, v34
	v_mfma_f32_16x16x4_f32 v[6:9], v93, v89, v[6:9]
	v_mfma_f32_16x16x4_f32 v[6:9], v94, v90, v[6:9]
	v_mfma_f32_16x16x4_f32 v[6:9], v95, v91, v[6:9]
	v_mfma_f32_16x16x4_f32 v[6:9], v100, v96, v[6:9]
	v_mul_f32_e64 v34, v100, v100
	v_mul_f32_e64 v35, v101, v101
	v_mul_f32_e64 v36, v102, v102
	v_mul_f32_e64 v37, v103, v103
	v_add_f32_e32 v34, v34, v35
	v_add_f32_e32 v34, v34, v36
	v_add_f32_e32 v34, v34, v37
	v_add_f32_e32 v0, v0, v34
	v_mfma_f32_16x16x4_f32 v[6:9], v101, v97, v[6:9]
	v_mfma_f32_16x16x4_f32 v[6:9], v102, v98, v[6:9]
	v_mfma_f32_16x16x4_f32 v[6:9], v103, v99, v[6:9]
	v_mfma_f32_16x16x4_f32 v[6:9], v108, v104, v[6:9]
	v_mul_f32_e64 v34, v108, v108
	v_mul_f32_e64 v35, v109, v109
	v_mul_f32_e64 v36, v110, v110
	v_mul_f32_e64 v37, v111, v111
	v_add_f32_e32 v34, v34, v35
	v_add_f32_e32 v34, v34, v36
	v_add_f32_e32 v34, v34, v37
	v_add_f32_e32 v0, v0, v34
	v_mfma_f32_16x16x4_f32 v[6:9], v109, v105, v[6:9]
	v_mfma_f32_16x16x4_f32 v[6:9], v110, v106, v[6:9]
	v_mfma_f32_16x16x4_f32 v[6:9], v111, v107, v[6:9]
	v_mfma_f32_16x16x4_f32 v[6:9], v116, v112, v[6:9]
	v_mul_f32_e64 v34, v116, v116
	v_mul_f32_e64 v35, v117, v117
	v_mul_f32_e64 v36, v118, v118
	v_mul_f32_e64 v37, v119, v119
	v_add_f32_e32 v34, v34, v35
	v_add_f32_e32 v34, v34, v36
	v_add_f32_e32 v34, v34, v37
	v_add_f32_e32 v0, v0, v34
	v_mfma_f32_16x16x4_f32 v[6:9], v117, v113, v[6:9]
	v_mfma_f32_16x16x4_f32 v[6:9], v118, v114, v[6:9]
	v_mfma_f32_16x16x4_f32 v[6:9], v119, v115, v[6:9]
	global_load_dword v88, v[16:17], off
	global_load_dword v89, v[16:17], off offset:64
	global_load_dword v90, v[16:17], off offset:128
	global_load_dword v91, v[16:17], off offset:192
	global_load_dwordx4 v[92:95], v[18:19], off
	global_load_dword v96, v[16:17], off offset:1024
	global_load_dword v97, v[16:17], off offset:1088
	global_load_dword v98, v[16:17], off offset:1152
	global_load_dword v99, v[16:17], off offset:1216
	global_load_dwordx4 v[100:103], v[18:19], off offset:64
	global_load_dword v104, v[16:17], off offset:2048
	global_load_dword v105, v[16:17], off offset:2112
	global_load_dword v106, v[16:17], off offset:2176
	global_load_dword v107, v[16:17], off offset:2240
	global_load_dwordx4 v[108:111], v[18:19], off offset:128
	global_load_dword v112, v[16:17], off offset:3072
	global_load_dword v113, v[16:17], off offset:3136
	global_load_dword v114, v[16:17], off offset:3200
	global_load_dword v115, v[16:17], off offset:3264
	global_load_dwordx4 v[116:119], v[18:19], off offset:192
	v_lshl_add_u64 v[16:17], v[16:17], 0, s[92:93]
	s_add_u32 s0, s0, 0x100
	s_addc_u32 s1, s1, 0
	v_lshl_add_u64 v[18:19], v[14:15], 0, s[0:1]
	s_waitcnt vmcnt(60)
	v_mfma_f32_16x16x4_f32 v[6:9], v124, v120, v[6:9]
	v_mul_f32_e64 v34, v124, v124
	v_mul_f32_e64 v35, v125, v125
	v_mul_f32_e64 v36, v126, v126
	v_mul_f32_e64 v37, v127, v127
	v_add_f32_e32 v34, v34, v35
	v_add_f32_e32 v34, v34, v36
	v_add_f32_e32 v34, v34, v37
	v_add_f32_e32 v0, v0, v34
	v_mfma_f32_16x16x4_f32 v[6:9], v125, v121, v[6:9]
	v_mfma_f32_16x16x4_f32 v[6:9], v126, v122, v[6:9]
	v_mfma_f32_16x16x4_f32 v[6:9], v127, v123, v[6:9]
	v_mfma_f32_16x16x4_f32 v[6:9], v132, v128, v[6:9]
	v_mul_f32_e64 v34, v132, v132
	v_mul_f32_e64 v35, v133, v133
	v_mul_f32_e64 v36, v134, v134
	v_mul_f32_e64 v37, v135, v135
	v_add_f32_e32 v34, v34, v35
	v_add_f32_e32 v34, v34, v36
	v_add_f32_e32 v34, v34, v37
	v_add_f32_e32 v0, v0, v34
	v_mfma_f32_16x16x4_f32 v[6:9], v133, v129, v[6:9]
	v_mfma_f32_16x16x4_f32 v[6:9], v134, v130, v[6:9]
	v_mfma_f32_16x16x4_f32 v[6:9], v135, v131, v[6:9]
	v_mfma_f32_16x16x4_f32 v[6:9], v140, v136, v[6:9]
	v_mul_f32_e64 v34, v140, v140
	v_mul_f32_e64 v35, v141, v141
	v_mul_f32_e64 v36, v142, v142
	v_mul_f32_e64 v37, v143, v143
	v_add_f32_e32 v34, v34, v35
	v_add_f32_e32 v34, v34, v36
	v_add_f32_e32 v34, v34, v37
	v_add_f32_e32 v0, v0, v34
	v_mfma_f32_16x16x4_f32 v[6:9], v141, v137, v[6:9]
	v_mfma_f32_16x16x4_f32 v[6:9], v142, v138, v[6:9]
	v_mfma_f32_16x16x4_f32 v[6:9], v143, v139, v[6:9]
	v_mfma_f32_16x16x4_f32 v[6:9], v148, v144, v[6:9]
	v_mul_f32_e64 v34, v148, v148
	v_mul_f32_e64 v35, v149, v149
	v_mul_f32_e64 v36, v150, v150
	v_mul_f32_e64 v37, v151, v151
	v_add_f32_e32 v34, v34, v35
	v_add_f32_e32 v34, v34, v36
	v_add_f32_e32 v34, v34, v37
	v_add_f32_e32 v0, v0, v34
	v_mfma_f32_16x16x4_f32 v[6:9], v149, v145, v[6:9]
	v_mfma_f32_16x16x4_f32 v[6:9], v150, v146, v[6:9]
	v_mfma_f32_16x16x4_f32 v[6:9], v151, v147, v[6:9]
	global_load_dword v120, v[16:17], off
	global_load_dword v121, v[16:17], off offset:64
	global_load_dword v122, v[16:17], off offset:128
	global_load_dword v123, v[16:17], off offset:192
	global_load_dwordx4 v[124:127], v[18:19], off
	global_load_dword v128, v[16:17], off offset:1024
	global_load_dword v129, v[16:17], off offset:1088
	global_load_dword v130, v[16:17], off offset:1152
	global_load_dword v131, v[16:17], off offset:1216
	global_load_dwordx4 v[132:135], v[18:19], off offset:64
	global_load_dword v136, v[16:17], off offset:2048
	global_load_dword v137, v[16:17], off offset:2112
	global_load_dword v138, v[16:17], off offset:2176
	global_load_dword v139, v[16:17], off offset:2240
	global_load_dwordx4 v[140:143], v[18:19], off offset:128
	global_load_dword v144, v[16:17], off offset:3072
	global_load_dword v145, v[16:17], off offset:3136
	global_load_dword v146, v[16:17], off offset:3200
	global_load_dword v147, v[16:17], off offset:3264
	global_load_dwordx4 v[148:151], v[18:19], off offset:192
	v_lshl_add_u64 v[16:17], v[16:17], 0, s[92:93]
	s_add_u32 s0, s0, 0x100
	s_addc_u32 s1, s1, 0
	v_lshl_add_u64 v[18:19], v[14:15], 0, s[0:1]
	s_waitcnt vmcnt(60)
; __device__ __forceinline__ void phase_router(const Params& p, int l, const float* xlat, const float* xctx, int nrows) {
;     ...
;     for (int s = 0; s < 64; ++s) {
;       const float4 a = *(const float4*)(xr + s * 16);
;       const float b0 = wp[s * 256], b1 = wp[s * 256 + 16], b2 = wp[s * 256 + 32], b3 = wp[s * 256 + 48];
;       ss += a.x * a.x + a.y * a.y + a.z * a.z + a.w * a.w;
;       acc = __builtin_amdgcn_mfma_f32_16x16x4f32(a.x, b0, acc, 0, 0, 0);
;       acc = __builtin_amdgcn_mfma_f32_16x16x4f32(a.y, b1, acc, 0, 0, 0);
;       acc = __builtin_amdgcn_mfma_f32_16x16x4f32(a.z, b2, acc, 0, 0, 0);
;       acc = __builtin_amdgcn_mfma_f32_16x16x4f32(a.w, b3, acc, 0, 0, 0);
;     }
	v_mfma_f32_16x16x4_f32 v[6:9], v156, v152, v[6:9]
	v_mul_f32_e64 v34, v156, v156
	v_mul_f32_e64 v35, v157, v157
	v_mul_f32_e64 v36, v158, v158
	v_mul_f32_e64 v37, v159, v159
	v_add_f32_e32 v34, v34, v35
	v_add_f32_e32 v34, v34, v36
	v_add_f32_e32 v34, v34, v37
	v_add_f32_e32 v0, v0, v34
	v_mfma_f32_16x16x4_f32 v[6:9], v157, v153, v[6:9]
	v_mfma_f32_16x16x4_f32 v[6:9], v158, v154, v[6:9]
	v_mfma_f32_16x16x4_f32 v[6:9], v159, v155, v[6:9]
	v_mfma_f32_16x16x4_f32 v[6:9], v164, v160, v[6:9]
	v_mul_f32_e64 v34, v164, v164
	v_mul_f32_e64 v35, v165, v165
	v_mul_f32_e64 v36, v166, v166
	v_mul_f32_e64 v37, v167, v167
	v_add_f32_e32 v34, v34, v35
	v_add_f32_e32 v34, v34, v36
	v_add_f32_e32 v34, v34, v37
	v_add_f32_e32 v0, v0, v34
	v_mfma_f32_16x16x4_f32 v[6:9], v165, v161, v[6:9]
	v_mfma_f32_16x16x4_f32 v[6:9], v166, v162, v[6:9]
	v_mfma_f32_16x16x4_f32 v[6:9], v167, v163, v[6:9]
	v_mfma_f32_16x16x4_f32 v[6:9], v172, v168, v[6:9]
	v_mul_f32_e64 v34, v172, v172
	v_mul_f32_e64 v35, v173, v173
	v_mul_f32_e64 v36, v174, v174
	v_mul_f32_e64 v37, v175, v175
	v_add_f32_e32 v34, v34, v35
	v_add_f32_e32 v34, v34, v36
	v_add_f32_e32 v34, v34, v37
	v_add_f32_e32 v0, v0, v34
	v_mfma_f32_16x16x4_f32 v[6:9], v173, v169, v[6:9]
	v_mfma_f32_16x16x4_f32 v[6:9], v174, v170, v[6:9]
	v_mfma_f32_16x16x4_f32 v[6:9], v175, v171, v[6:9]
	v_mfma_f32_16x16x4_f32 v[6:9], v180, v176, v[6:9]
	v_mul_f32_e64 v34, v180, v180
	v_mul_f32_e64 v35, v181, v181
	v_mul_f32_e64 v36, v182, v182
	v_mul_f32_e64 v37, v183, v183
	v_add_f32_e32 v34, v34, v35
	v_add_f32_e32 v34, v34, v36
	v_add_f32_e32 v34, v34, v37
	v_add_f32_e32 v0, v0, v34
	v_mfma_f32_16x16x4_f32 v[6:9], v181, v177, v[6:9]
	v_mfma_f32_16x16x4_f32 v[6:9], v182, v178, v[6:9]
	v_mfma_f32_16x16x4_f32 v[6:9], v183, v179, v[6:9]
	global_load_dword v152, v[16:17], off
	global_load_dword v153, v[16:17], off offset:64
	global_load_dword v154, v[16:17], off offset:128
	global_load_dword v155, v[16:17], off offset:192
	global_load_dwordx4 v[156:159], v[18:19], off
	global_load_dword v160, v[16:17], off offset:1024
	global_load_dword v161, v[16:17], off offset:1088
	global_load_dword v162, v[16:17], off offset:1152
	global_load_dword v163, v[16:17], off offset:1216
	global_load_dwordx4 v[164:167], v[18:19], off offset:64
	global_load_dword v168, v[16:17], off offset:2048
	global_load_dword v169, v[16:17], off offset:2112
	global_load_dword v170, v[16:17], off offset:2176
	global_load_dword v171, v[16:17], off offset:2240
	global_load_dwordx4 v[172:175], v[18:19], off offset:128
	global_load_dword v176, v[16:17], off offset:3072
	global_load_dword v177, v[16:17], off offset:3136
	global_load_dword v178, v[16:17], off offset:3200
	global_load_dword v179, v[16:17], off offset:3264
	global_load_dwordx4 v[180:183], v[18:19], off offset:192
	v_lshl_add_u64 v[16:17], v[16:17], 0, s[92:93]
	s_add_u32 s0, s0, 0x100
	s_addc_u32 s1, s1, 0
	v_lshl_add_u64 v[18:19], v[14:15], 0, s[0:1]
	s_waitcnt vmcnt(60)
	v_mfma_f32_16x16x4_f32 v[6:9], v42, v38, v[6:9]
	v_mul_f32_e64 v34, v42, v42
	v_mul_f32_e64 v35, v43, v43
	v_mul_f32_e64 v36, v44, v44
	v_mul_f32_e64 v37, v45, v45
	v_add_f32_e32 v34, v34, v35
	v_add_f32_e32 v34, v34, v36
	v_add_f32_e32 v34, v34, v37
	v_add_f32_e32 v0, v0, v34
	v_mfma_f32_16x16x4_f32 v[6:9], v43, v39, v[6:9]
	v_mfma_f32_16x16x4_f32 v[6:9], v44, v40, v[6:9]
	v_mfma_f32_16x16x4_f32 v[6:9], v45, v41, v[6:9]
	v_mfma_f32_16x16x4_f32 v[6:9], v58, v54, v[6:9]
	v_mul_f32_e64 v34, v58, v58
	v_mul_f32_e64 v35, v59, v59
	v_mul_f32_e64 v36, v60, v60
	v_mul_f32_e64 v37, v61, v61
	v_add_f32_e32 v34, v34, v35
	v_add_f32_e32 v34, v34, v36
	v_add_f32_e32 v34, v34, v37
	v_add_f32_e32 v0, v0, v34
	v_mfma_f32_16x16x4_f32 v[6:9], v59, v55, v[6:9]
	v_mfma_f32_16x16x4_f32 v[6:9], v60, v56, v[6:9]
	v_mfma_f32_16x16x4_f32 v[6:9], v61, v57, v[6:9]
	v_mfma_f32_16x16x4_f32 v[6:9], v66, v62, v[6:9]
	v_mul_f32_e64 v34, v66, v66
	v_mul_f32_e64 v35, v67, v67
	v_mul_f32_e64 v36, v68, v68
	v_mul_f32_e64 v37, v69, v69
	v_add_f32_e32 v34, v34, v35
	v_add_f32_e32 v34, v34, v36
	v_add_f32_e32 v34, v34, v37
	v_add_f32_e32 v0, v0, v34
	v_mfma_f32_16x16x4_f32 v[6:9], v67, v63, v[6:9]
	v_mfma_f32_16x16x4_f32 v[6:9], v68, v64, v[6:9]
	v_mfma_f32_16x16x4_f32 v[6:9], v69, v65, v[6:9]
	v_mfma_f32_16x16x4_f32 v[6:9], v74, v70, v[6:9]
	v_mul_f32_e64 v34, v74, v74
	v_mul_f32_e64 v35, v75, v75
	v_mul_f32_e64 v36, v76, v76
	v_mul_f32_e64 v37, v77, v77
	v_add_f32_e32 v34, v34, v35
	v_add_f32_e32 v34, v34, v36
	v_add_f32_e32 v34, v34, v37
	v_add_f32_e32 v0, v0, v34
	v_mfma_f32_16x16x4_f32 v[6:9], v75, v71, v[6:9]
	v_mfma_f32_16x16x4_f32 v[6:9], v76, v72, v[6:9]
	v_mfma_f32_16x16x4_f32 v[6:9], v77, v73, v[6:9]
	global_load_dword v38, v[16:17], off
	global_load_dword v39, v[16:17], off offset:64
	global_load_dword v40, v[16:17], off offset:128
	global_load_dword v41, v[16:17], off offset:192
	global_load_dwordx4 v[42:45], v[18:19], off
	global_load_dword v54, v[16:17], off offset:1024
	global_load_dword v55, v[16:17], off offset:1088
	global_load_dword v56, v[16:17], off offset:1152
	global_load_dword v57, v[16:17], off offset:1216
	global_load_dwordx4 v[58:61], v[18:19], off offset:64
	global_load_dword v62, v[16:17], off offset:2048
	global_load_dword v63, v[16:17], off offset:2112
	global_load_dword v64, v[16:17], off offset:2176
	global_load_dword v65, v[16:17], off offset:2240
	global_load_dwordx4 v[66:69], v[18:19], off offset:128
	global_load_dword v70, v[16:17], off offset:3072
	global_load_dword v71, v[16:17], off offset:3136
	global_load_dword v72, v[16:17], off offset:3200
	global_load_dword v73, v[16:17], off offset:3264
	global_load_dwordx4 v[74:77], v[18:19], off offset:192
	v_lshl_add_u64 v[16:17], v[16:17], 0, s[92:93]
	s_add_u32 s0, s0, 0x100
	s_addc_u32 s1, s1, 0
	v_lshl_add_u64 v[18:19], v[14:15], 0, s[0:1]
	s_waitcnt vmcnt(60)
; __device__ __forceinline__ void phase_router(const Params& p, int l, const float* xlat, const float* xctx, int nrows) {
;     ...
;     for (int s = 0; s < 64; ++s) {
;       const float4 a = *(const float4*)(xr + s * 16);
;       const float b0 = wp[s * 256], b1 = wp[s * 256 + 16], b2 = wp[s * 256 + 32], b3 = wp[s * 256 + 48];
;       ss += a.x * a.x + a.y * a.y + a.z * a.z + a.w * a.w;
;       acc = __builtin_amdgcn_mfma_f32_16x16x4f32(a.x, b0, acc, 0, 0, 0);
;       acc = __builtin_amdgcn_mfma_f32_16x16x4f32(a.y, b1, acc, 0, 0, 0);
;       acc = __builtin_amdgcn_mfma_f32_16x16x4f32(a.z, b2, acc, 0, 0, 0);
;       acc = __builtin_amdgcn_mfma_f32_16x16x4f32(a.w, b3, acc, 0, 0, 0);
;     }
	v_mfma_f32_16x16x4_f32 v[6:9], v92, v88, v[6:9]
	v_mul_f32_e64 v34, v92, v92
	v_mul_f32_e64 v35, v93, v93
	v_mul_f32_e64 v36, v94, v94
	v_mul_f32_e64 v37, v95, v95
	v_add_f32_e32 v34, v34, v35
	v_add_f32_e32 v34, v34, v36
	v_add_f32_e32 v34, v34, v37
	v_add_f32_e32 v0, v0, v34
	v_mfma_f32_16x16x4_f32 v[6:9], v93, v89, v[6:9]
	v_mfma_f32_16x16x4_f32 v[6:9], v94, v90, v[6:9]
	v_mfma_f32_16x16x4_f32 v[6:9], v95, v91, v[6:9]
	v_mfma_f32_16x16x4_f32 v[6:9], v100, v96, v[6:9]
	v_mul_f32_e64 v34, v100, v100
	v_mul_f32_e64 v35, v101, v101
	v_mul_f32_e64 v36, v102, v102
	v_mul_f32_e64 v37, v103, v103
	v_add_f32_e32 v34, v34, v35
	v_add_f32_e32 v34, v34, v36
	v_add_f32_e32 v34, v34, v37
	v_add_f32_e32 v0, v0, v34
	v_mfma_f32_16x16x4_f32 v[6:9], v101, v97, v[6:9]
	v_mfma_f32_16x16x4_f32 v[6:9], v102, v98, v[6:9]
	v_mfma_f32_16x16x4_f32 v[6:9], v103, v99, v[6:9]
	v_mfma_f32_16x16x4_f32 v[6:9], v108, v104, v[6:9]
	v_mul_f32_e64 v34, v108, v108
	v_mul_f32_e64 v35, v109, v109
	v_mul_f32_e64 v36, v110, v110
	v_mul_f32_e64 v37, v111, v111
	v_add_f32_e32 v34, v34, v35
	v_add_f32_e32 v34, v34, v36
	v_add_f32_e32 v34, v34, v37
	v_add_f32_e32 v0, v0, v34
	v_mfma_f32_16x16x4_f32 v[6:9], v109, v105, v[6:9]
	v_mfma_f32_16x16x4_f32 v[6:9], v110, v106, v[6:9]
	v_mfma_f32_16x16x4_f32 v[6:9], v111, v107, v[6:9]
	v_mfma_f32_16x16x4_f32 v[6:9], v116, v112, v[6:9]
	v_mul_f32_e64 v34, v116, v116
	v_mul_f32_e64 v35, v117, v117
	v_mul_f32_e64 v36, v118, v118
	v_mul_f32_e64 v37, v119, v119
	v_add_f32_e32 v34, v34, v35
	v_add_f32_e32 v34, v34, v36
	v_add_f32_e32 v34, v34, v37
	v_add_f32_e32 v0, v0, v34
	v_mfma_f32_16x16x4_f32 v[6:9], v117, v113, v[6:9]
	v_mfma_f32_16x16x4_f32 v[6:9], v118, v114, v[6:9]
	v_mfma_f32_16x16x4_f32 v[6:9], v119, v115, v[6:9]
	global_load_dword v88, v[16:17], off
	global_load_dword v89, v[16:17], off offset:64
	global_load_dword v90, v[16:17], off offset:128
	global_load_dword v91, v[16:17], off offset:192
	global_load_dwordx4 v[92:95], v[18:19], off
	global_load_dword v96, v[16:17], off offset:1024
	global_load_dword v97, v[16:17], off offset:1088
	global_load_dword v98, v[16:17], off offset:1152
	global_load_dword v99, v[16:17], off offset:1216
	global_load_dwordx4 v[100:103], v[18:19], off offset:64
	global_load_dword v104, v[16:17], off offset:2048
	global_load_dword v105, v[16:17], off offset:2112
	global_load_dword v106, v[16:17], off offset:2176
	global_load_dword v107, v[16:17], off offset:2240
	global_load_dwordx4 v[108:111], v[18:19], off offset:128
	global_load_dword v112, v[16:17], off offset:3072
	global_load_dword v113, v[16:17], off offset:3136
	global_load_dword v114, v[16:17], off offset:3200
	global_load_dword v115, v[16:17], off offset:3264
	global_load_dwordx4 v[116:119], v[18:19], off offset:192
	v_lshl_add_u64 v[16:17], v[16:17], 0, s[92:93]
	s_add_u32 s0, s0, 0x100
	s_addc_u32 s1, s1, 0
	v_lshl_add_u64 v[18:19], v[14:15], 0, s[0:1]
	s_waitcnt vmcnt(60)
	v_mfma_f32_16x16x4_f32 v[6:9], v124, v120, v[6:9]
	v_mul_f32_e64 v34, v124, v124
	v_mul_f32_e64 v35, v125, v125
	v_mul_f32_e64 v36, v126, v126
	v_mul_f32_e64 v37, v127, v127
	v_add_f32_e32 v34, v34, v35
	v_add_f32_e32 v34, v34, v36
	v_add_f32_e32 v34, v34, v37
	v_add_f32_e32 v0, v0, v34
	v_mfma_f32_16x16x4_f32 v[6:9], v125, v121, v[6:9]
	v_mfma_f32_16x16x4_f32 v[6:9], v126, v122, v[6:9]
	v_mfma_f32_16x16x4_f32 v[6:9], v127, v123, v[6:9]
	v_mfma_f32_16x16x4_f32 v[6:9], v132, v128, v[6:9]
	v_mul_f32_e64 v34, v132, v132
	v_mul_f32_e64 v35, v133, v133
	v_mul_f32_e64 v36, v134, v134
	v_mul_f32_e64 v37, v135, v135
	v_add_f32_e32 v34, v34, v35
	v_add_f32_e32 v34, v34, v36
	v_add_f32_e32 v34, v34, v37
	v_add_f32_e32 v0, v0, v34
	v_mfma_f32_16x16x4_f32 v[6:9], v133, v129, v[6:9]
	v_mfma_f32_16x16x4_f32 v[6:9], v134, v130, v[6:9]
	v_mfma_f32_16x16x4_f32 v[6:9], v135, v131, v[6:9]
	v_mfma_f32_16x16x4_f32 v[6:9], v140, v136, v[6:9]
	v_mul_f32_e64 v34, v140, v140
	v_mul_f32_e64 v35, v141, v141
	v_mul_f32_e64 v36, v142, v142
	v_mul_f32_e64 v37, v143, v143
	v_add_f32_e32 v34, v34, v35
	v_add_f32_e32 v34, v34, v36
	v_add_f32_e32 v34, v34, v37
	v_add_f32_e32 v0, v0, v34
	v_mfma_f32_16x16x4_f32 v[6:9], v141, v137, v[6:9]
	v_mfma_f32_16x16x4_f32 v[6:9], v142, v138, v[6:9]
	v_mfma_f32_16x16x4_f32 v[6:9], v143, v139, v[6:9]
	v_mfma_f32_16x16x4_f32 v[6:9], v148, v144, v[6:9]
	v_mul_f32_e64 v34, v148, v148
	v_mul_f32_e64 v35, v149, v149
	v_mul_f32_e64 v36, v150, v150
	v_mul_f32_e64 v37, v151, v151
	v_add_f32_e32 v34, v34, v35
	v_add_f32_e32 v34, v34, v36
	v_add_f32_e32 v34, v34, v37
	v_add_f32_e32 v0, v0, v34
	v_mfma_f32_16x16x4_f32 v[6:9], v149, v145, v[6:9]
	v_mfma_f32_16x16x4_f32 v[6:9], v150, v146, v[6:9]
	v_mfma_f32_16x16x4_f32 v[6:9], v151, v147, v[6:9]
	global_load_dword v120, v[16:17], off
	global_load_dword v121, v[16:17], off offset:64
	global_load_dword v122, v[16:17], off offset:128
	global_load_dword v123, v[16:17], off offset:192
	global_load_dwordx4 v[124:127], v[18:19], off
	global_load_dword v128, v[16:17], off offset:1024
	global_load_dword v129, v[16:17], off offset:1088
	global_load_dword v130, v[16:17], off offset:1152
	global_load_dword v131, v[16:17], off offset:1216
	global_load_dwordx4 v[132:135], v[18:19], off offset:64
	global_load_dword v136, v[16:17], off offset:2048
	global_load_dword v137, v[16:17], off offset:2112
	global_load_dword v138, v[16:17], off offset:2176
	global_load_dword v139, v[16:17], off offset:2240
	global_load_dwordx4 v[140:143], v[18:19], off offset:128
	global_load_dword v144, v[16:17], off offset:3072
	global_load_dword v145, v[16:17], off offset:3136
	global_load_dword v146, v[16:17], off offset:3200
	global_load_dword v147, v[16:17], off offset:3264
	global_load_dwordx4 v[148:151], v[18:19], off offset:192
	v_lshl_add_u64 v[16:17], v[16:17], 0, s[92:93]
	s_add_u32 s0, s0, 0x100
	s_addc_u32 s1, s1, 0
	v_lshl_add_u64 v[18:19], v[14:15], 0, s[0:1]
	s_waitcnt vmcnt(60)
; __device__ __forceinline__ void phase_router(const Params& p, int l, const float* xlat, const float* xctx, int nrows) {
;     ...
;     for (int s = 0; s < 64; ++s) {
;       const float4 a = *(const float4*)(xr + s * 16);
;       const float b0 = wp[s * 256], b1 = wp[s * 256 + 16], b2 = wp[s * 256 + 32], b3 = wp[s * 256 + 48];
;       ss += a.x * a.x + a.y * a.y + a.z * a.z + a.w * a.w;
;       acc = __builtin_amdgcn_mfma_f32_16x16x4f32(a.x, b0, acc, 0, 0, 0);
;       acc = __builtin_amdgcn_mfma_f32_16x16x4f32(a.y, b1, acc, 0, 0, 0);
;       acc = __builtin_amdgcn_mfma_f32_16x16x4f32(a.z, b2, acc, 0, 0, 0);
;       acc = __builtin_amdgcn_mfma_f32_16x16x4f32(a.w, b3, acc, 0, 0, 0);
;     }
	v_mfma_f32_16x16x4_f32 v[6:9], v156, v152, v[6:9]
	v_mul_f32_e64 v34, v156, v156
	v_mul_f32_e64 v35, v157, v157
	v_mul_f32_e64 v36, v158, v158
	v_mul_f32_e64 v37, v159, v159
	v_add_f32_e32 v34, v34, v35
	v_add_f32_e32 v34, v34, v36
	v_add_f32_e32 v34, v34, v37
	v_add_f32_e32 v0, v0, v34
	v_mfma_f32_16x16x4_f32 v[6:9], v157, v153, v[6:9]
	v_mfma_f32_16x16x4_f32 v[6:9], v158, v154, v[6:9]
	v_mfma_f32_16x16x4_f32 v[6:9], v159, v155, v[6:9]
	v_mfma_f32_16x16x4_f32 v[6:9], v164, v160, v[6:9]
	v_mul_f32_e64 v34, v164, v164
	v_mul_f32_e64 v35, v165, v165
	v_mul_f32_e64 v36, v166, v166
	v_mul_f32_e64 v37, v167, v167
	v_add_f32_e32 v34, v34, v35
	v_add_f32_e32 v34, v34, v36
	v_add_f32_e32 v34, v34, v37
	v_add_f32_e32 v0, v0, v34
	v_mfma_f32_16x16x4_f32 v[6:9], v165, v161, v[6:9]
	v_mfma_f32_16x16x4_f32 v[6:9], v166, v162, v[6:9]
	v_mfma_f32_16x16x4_f32 v[6:9], v167, v163, v[6:9]
	v_mfma_f32_16x16x4_f32 v[6:9], v172, v168, v[6:9]
	v_mul_f32_e64 v34, v172, v172
	v_mul_f32_e64 v35, v173, v173
	v_mul_f32_e64 v36, v174, v174
	v_mul_f32_e64 v37, v175, v175
	v_add_f32_e32 v34, v34, v35
	v_add_f32_e32 v34, v34, v36
	v_add_f32_e32 v34, v34, v37
	v_add_f32_e32 v0, v0, v34
	v_mfma_f32_16x16x4_f32 v[6:9], v173, v169, v[6:9]
	v_mfma_f32_16x16x4_f32 v[6:9], v174, v170, v[6:9]
	v_mfma_f32_16x16x4_f32 v[6:9], v175, v171, v[6:9]
	v_mfma_f32_16x16x4_f32 v[6:9], v180, v176, v[6:9]
	v_mul_f32_e64 v34, v180, v180
	v_mul_f32_e64 v35, v181, v181
	v_mul_f32_e64 v36, v182, v182
	v_mul_f32_e64 v37, v183, v183
	v_add_f32_e32 v34, v34, v35
	v_add_f32_e32 v34, v34, v36
	v_add_f32_e32 v34, v34, v37
	v_add_f32_e32 v0, v0, v34
	v_mfma_f32_16x16x4_f32 v[6:9], v181, v177, v[6:9]
	v_mfma_f32_16x16x4_f32 v[6:9], v182, v178, v[6:9]
	v_mfma_f32_16x16x4_f32 v[6:9], v183, v179, v[6:9]
	global_load_dword v152, v[16:17], off
	global_load_dword v153, v[16:17], off offset:64
	global_load_dword v154, v[16:17], off offset:128
	global_load_dword v155, v[16:17], off offset:192
	global_load_dwordx4 v[156:159], v[18:19], off
	global_load_dword v160, v[16:17], off offset:1024
	global_load_dword v161, v[16:17], off offset:1088
	global_load_dword v162, v[16:17], off offset:1152
	global_load_dword v163, v[16:17], off offset:1216
	global_load_dwordx4 v[164:167], v[18:19], off offset:64
	global_load_dword v168, v[16:17], off offset:2048
	global_load_dword v169, v[16:17], off offset:2112
	global_load_dword v170, v[16:17], off offset:2176
	global_load_dword v171, v[16:17], off offset:2240
	global_load_dwordx4 v[172:175], v[18:19], off offset:128
	global_load_dword v176, v[16:17], off offset:3072
	global_load_dword v177, v[16:17], off offset:3136
	global_load_dword v178, v[16:17], off offset:3200
	global_load_dword v179, v[16:17], off offset:3264
	global_load_dwordx4 v[180:183], v[18:19], off offset:192
	v_lshl_add_u64 v[16:17], v[16:17], 0, s[92:93]
	s_add_u32 s0, s0, 0x100
	s_addc_u32 s1, s1, 0
	v_lshl_add_u64 v[18:19], v[14:15], 0, s[0:1]
	s_waitcnt vmcnt(60)
	v_mfma_f32_16x16x4_f32 v[6:9], v42, v38, v[6:9]
	v_mul_f32_e64 v34, v42, v42
	v_mul_f32_e64 v35, v43, v43
	v_mul_f32_e64 v36, v44, v44
	v_mul_f32_e64 v37, v45, v45
	v_add_f32_e32 v34, v34, v35
	v_add_f32_e32 v34, v34, v36
	v_add_f32_e32 v34, v34, v37
	v_add_f32_e32 v0, v0, v34
	v_mfma_f32_16x16x4_f32 v[6:9], v43, v39, v[6:9]
	v_mfma_f32_16x16x4_f32 v[6:9], v44, v40, v[6:9]
	v_mfma_f32_16x16x4_f32 v[6:9], v45, v41, v[6:9]
	v_mfma_f32_16x16x4_f32 v[6:9], v58, v54, v[6:9]
	v_mul_f32_e64 v34, v58, v58
	v_mul_f32_e64 v35, v59, v59
	v_mul_f32_e64 v36, v60, v60
	v_mul_f32_e64 v37, v61, v61
	v_add_f32_e32 v34, v34, v35
	v_add_f32_e32 v34, v34, v36
	v_add_f32_e32 v34, v34, v37
	v_add_f32_e32 v0, v0, v34
	v_mfma_f32_16x16x4_f32 v[6:9], v59, v55, v[6:9]
	v_mfma_f32_16x16x4_f32 v[6:9], v60, v56, v[6:9]
	v_mfma_f32_16x16x4_f32 v[6:9], v61, v57, v[6:9]
	v_mfma_f32_16x16x4_f32 v[6:9], v66, v62, v[6:9]
	v_mul_f32_e64 v34, v66, v66
	v_mul_f32_e64 v35, v67, v67
	v_mul_f32_e64 v36, v68, v68
	v_mul_f32_e64 v37, v69, v69
	v_add_f32_e32 v34, v34, v35
	v_add_f32_e32 v34, v34, v36
	v_add_f32_e32 v34, v34, v37
	v_add_f32_e32 v0, v0, v34
	v_mfma_f32_16x16x4_f32 v[6:9], v67, v63, v[6:9]
	v_mfma_f32_16x16x4_f32 v[6:9], v68, v64, v[6:9]
	v_mfma_f32_16x16x4_f32 v[6:9], v69, v65, v[6:9]
	v_mfma_f32_16x16x4_f32 v[6:9], v74, v70, v[6:9]
	v_mul_f32_e64 v34, v74, v74
	v_mul_f32_e64 v35, v75, v75
	v_mul_f32_e64 v36, v76, v76
	v_mul_f32_e64 v37, v77, v77
	v_add_f32_e32 v34, v34, v35
	v_add_f32_e32 v34, v34, v36
	v_add_f32_e32 v34, v34, v37
	v_add_f32_e32 v0, v0, v34
	v_mfma_f32_16x16x4_f32 v[6:9], v75, v71, v[6:9]
	v_mfma_f32_16x16x4_f32 v[6:9], v76, v72, v[6:9]
	v_mfma_f32_16x16x4_f32 v[6:9], v77, v73, v[6:9]
	global_load_dword v38, v[16:17], off
	global_load_dword v39, v[16:17], off offset:64
	global_load_dword v40, v[16:17], off offset:128
	global_load_dword v41, v[16:17], off offset:192
	global_load_dwordx4 v[42:45], v[18:19], off
	global_load_dword v54, v[16:17], off offset:1024
	global_load_dword v55, v[16:17], off offset:1088
	global_load_dword v56, v[16:17], off offset:1152
	global_load_dword v57, v[16:17], off offset:1216
	global_load_dwordx4 v[58:61], v[18:19], off offset:64
	global_load_dword v62, v[16:17], off offset:2048
	global_load_dword v63, v[16:17], off offset:2112
	global_load_dword v64, v[16:17], off offset:2176
	global_load_dword v65, v[16:17], off offset:2240
	global_load_dwordx4 v[66:69], v[18:19], off offset:128
	global_load_dword v70, v[16:17], off offset:3072
	global_load_dword v71, v[16:17], off offset:3136
	global_load_dword v72, v[16:17], off offset:3200
	global_load_dword v73, v[16:17], off offset:3264
	global_load_dwordx4 v[74:77], v[18:19], off offset:192
	v_lshl_add_u64 v[16:17], v[16:17], 0, s[92:93]
	s_add_u32 s0, s0, 0x100
	s_addc_u32 s1, s1, 0
	v_lshl_add_u64 v[18:19], v[14:15], 0, s[0:1]
	s_waitcnt vmcnt(60)
; __device__ __forceinline__ void phase_router(const Params& p, int l, const float* xlat, const float* xctx, int nrows) {
;     ...
;     for (int s = 0; s < 64; ++s) {
;       const float4 a = *(const float4*)(xr + s * 16);
;       const float b0 = wp[s * 256], b1 = wp[s * 256 + 16], b2 = wp[s * 256 + 32], b3 = wp[s * 256 + 48];
;       ss += a.x * a.x + a.y * a.y + a.z * a.z + a.w * a.w;
;       acc = __builtin_amdgcn_mfma_f32_16x16x4f32(a.x, b0, acc, 0, 0, 0);
;       acc = __builtin_amdgcn_mfma_f32_16x16x4f32(a.y, b1, acc, 0, 0, 0);
;       acc = __builtin_amdgcn_mfma_f32_16x16x4f32(a.z, b2, acc, 0, 0, 0);
;       acc = __builtin_amdgcn_mfma_f32_16x16x4f32(a.w, b3, acc, 0, 0, 0);
;     }
	v_mfma_f32_16x16x4_f32 v[6:9], v92, v88, v[6:9]
	v_mul_f32_e64 v34, v92, v92
	v_mul_f32_e64 v35, v93, v93
	v_mul_f32_e64 v36, v94, v94
	v_mul_f32_e64 v37, v95, v95
	v_add_f32_e32 v34, v34, v35
	v_add_f32_e32 v34, v34, v36
	v_add_f32_e32 v34, v34, v37
	v_add_f32_e32 v0, v0, v34
	v_mfma_f32_16x16x4_f32 v[6:9], v93, v89, v[6:9]
	v_mfma_f32_16x16x4_f32 v[6:9], v94, v90, v[6:9]
	v_mfma_f32_16x16x4_f32 v[6:9], v95, v91, v[6:9]
	v_mfma_f32_16x16x4_f32 v[6:9], v100, v96, v[6:9]
	v_mul_f32_e64 v34, v100, v100
	v_mul_f32_e64 v35, v101, v101
	v_mul_f32_e64 v36, v102, v102
	v_mul_f32_e64 v37, v103, v103
	v_add_f32_e32 v34, v34, v35
	v_add_f32_e32 v34, v34, v36
	v_add_f32_e32 v34, v34, v37
	v_add_f32_e32 v0, v0, v34
	v_mfma_f32_16x16x4_f32 v[6:9], v101, v97, v[6:9]
	v_mfma_f32_16x16x4_f32 v[6:9], v102, v98, v[6:9]
	v_mfma_f32_16x16x4_f32 v[6:9], v103, v99, v[6:9]
	v_mfma_f32_16x16x4_f32 v[6:9], v108, v104, v[6:9]
	v_mul_f32_e64 v34, v108, v108
	v_mul_f32_e64 v35, v109, v109
	v_mul_f32_e64 v36, v110, v110
	v_mul_f32_e64 v37, v111, v111
	v_add_f32_e32 v34, v34, v35
	v_add_f32_e32 v34, v34, v36
	v_add_f32_e32 v34, v34, v37
	v_add_f32_e32 v0, v0, v34
	v_mfma_f32_16x16x4_f32 v[6:9], v109, v105, v[6:9]
	v_mfma_f32_16x16x4_f32 v[6:9], v110, v106, v[6:9]
	v_mfma_f32_16x16x4_f32 v[6:9], v111, v107, v[6:9]
	v_mfma_f32_16x16x4_f32 v[6:9], v116, v112, v[6:9]
	v_mul_f32_e64 v34, v116, v116
	v_mul_f32_e64 v35, v117, v117
	v_mul_f32_e64 v36, v118, v118
	v_mul_f32_e64 v37, v119, v119
	v_add_f32_e32 v34, v34, v35
	v_add_f32_e32 v34, v34, v36
	v_add_f32_e32 v34, v34, v37
	v_add_f32_e32 v0, v0, v34
	v_mfma_f32_16x16x4_f32 v[6:9], v117, v113, v[6:9]
	v_mfma_f32_16x16x4_f32 v[6:9], v118, v114, v[6:9]
	v_mfma_f32_16x16x4_f32 v[6:9], v119, v115, v[6:9]
	s_waitcnt vmcnt(40)
	v_mfma_f32_16x16x4_f32 v[6:9], v124, v120, v[6:9]
	v_mul_f32_e64 v34, v124, v124
	v_mul_f32_e64 v35, v125, v125
	v_mul_f32_e64 v36, v126, v126
	v_mul_f32_e64 v37, v127, v127
	v_add_f32_e32 v34, v34, v35
	v_add_f32_e32 v34, v34, v36
	v_add_f32_e32 v34, v34, v37
	v_add_f32_e32 v0, v0, v34
	v_mfma_f32_16x16x4_f32 v[6:9], v125, v121, v[6:9]
	v_mfma_f32_16x16x4_f32 v[6:9], v126, v122, v[6:9]
	v_mfma_f32_16x16x4_f32 v[6:9], v127, v123, v[6:9]
	v_mfma_f32_16x16x4_f32 v[6:9], v132, v128, v[6:9]
	v_mul_f32_e64 v34, v132, v132
	v_mul_f32_e64 v35, v133, v133
	v_mul_f32_e64 v36, v134, v134
	v_mul_f32_e64 v37, v135, v135
	v_add_f32_e32 v34, v34, v35
	v_add_f32_e32 v34, v34, v36
	v_add_f32_e32 v34, v34, v37
	v_add_f32_e32 v0, v0, v34
	v_mfma_f32_16x16x4_f32 v[6:9], v133, v129, v[6:9]
	v_mfma_f32_16x16x4_f32 v[6:9], v134, v130, v[6:9]
	v_mfma_f32_16x16x4_f32 v[6:9], v135, v131, v[6:9]
	v_mfma_f32_16x16x4_f32 v[6:9], v140, v136, v[6:9]
	v_mul_f32_e64 v34, v140, v140
	v_mul_f32_e64 v35, v141, v141
	v_mul_f32_e64 v36, v142, v142
	v_mul_f32_e64 v37, v143, v143
	v_add_f32_e32 v34, v34, v35
	v_add_f32_e32 v34, v34, v36
	v_add_f32_e32 v34, v34, v37
	v_add_f32_e32 v0, v0, v34
	v_mfma_f32_16x16x4_f32 v[6:9], v141, v137, v[6:9]
	v_mfma_f32_16x16x4_f32 v[6:9], v142, v138, v[6:9]
	v_mfma_f32_16x16x4_f32 v[6:9], v143, v139, v[6:9]
	v_mfma_f32_16x16x4_f32 v[6:9], v148, v144, v[6:9]
	v_mul_f32_e64 v34, v148, v148
	v_mul_f32_e64 v35, v149, v149
	v_mul_f32_e64 v36, v150, v150
	v_mul_f32_e64 v37, v151, v151
	v_add_f32_e32 v34, v34, v35
	v_add_f32_e32 v34, v34, v36
	v_add_f32_e32 v34, v34, v37
	v_add_f32_e32 v0, v0, v34
	v_mfma_f32_16x16x4_f32 v[6:9], v149, v145, v[6:9]
	v_mfma_f32_16x16x4_f32 v[6:9], v150, v146, v[6:9]
	v_mfma_f32_16x16x4_f32 v[6:9], v151, v147, v[6:9]
	s_waitcnt vmcnt(20)
	v_mfma_f32_16x16x4_f32 v[6:9], v156, v152, v[6:9]
	v_mul_f32_e64 v34, v156, v156
	v_mul_f32_e64 v35, v157, v157
	v_mul_f32_e64 v36, v158, v158
	v_mul_f32_e64 v37, v159, v159
	v_add_f32_e32 v34, v34, v35
	v_add_f32_e32 v34, v34, v36
	v_add_f32_e32 v34, v34, v37
	v_add_f32_e32 v0, v0, v34
	v_mfma_f32_16x16x4_f32 v[6:9], v157, v153, v[6:9]
	v_mfma_f32_16x16x4_f32 v[6:9], v158, v154, v[6:9]
	v_mfma_f32_16x16x4_f32 v[6:9], v159, v155, v[6:9]
	v_mfma_f32_16x16x4_f32 v[6:9], v164, v160, v[6:9]
	v_mul_f32_e64 v34, v164, v164
	v_mul_f32_e64 v35, v165, v165
	v_mul_f32_e64 v36, v166, v166
	v_mul_f32_e64 v37, v167, v167
	v_add_f32_e32 v34, v34, v35
	v_add_f32_e32 v34, v34, v36
	v_add_f32_e32 v34, v34, v37
	v_add_f32_e32 v0, v0, v34
	v_mfma_f32_16x16x4_f32 v[6:9], v165, v161, v[6:9]
	v_mfma_f32_16x16x4_f32 v[6:9], v166, v162, v[6:9]
	v_mfma_f32_16x16x4_f32 v[6:9], v167, v163, v[6:9]
	v_mfma_f32_16x16x4_f32 v[6:9], v172, v168, v[6:9]
	v_mul_f32_e64 v34, v172, v172
	v_mul_f32_e64 v35, v173, v173
	v_mul_f32_e64 v36, v174, v174
	v_mul_f32_e64 v37, v175, v175
	v_add_f32_e32 v34, v34, v35
	v_add_f32_e32 v34, v34, v36
	v_add_f32_e32 v34, v34, v37
	v_add_f32_e32 v0, v0, v34
	v_mfma_f32_16x16x4_f32 v[6:9], v173, v169, v[6:9]
	v_mfma_f32_16x16x4_f32 v[6:9], v174, v170, v[6:9]
	v_mfma_f32_16x16x4_f32 v[6:9], v175, v171, v[6:9]
	v_mfma_f32_16x16x4_f32 v[6:9], v180, v176, v[6:9]
	v_mul_f32_e64 v34, v180, v180
	v_mul_f32_e64 v35, v181, v181
	v_mul_f32_e64 v36, v182, v182
	v_mul_f32_e64 v37, v183, v183
	v_add_f32_e32 v34, v34, v35
	v_add_f32_e32 v34, v34, v36
	v_add_f32_e32 v34, v34, v37
	v_add_f32_e32 v0, v0, v34
	v_mfma_f32_16x16x4_f32 v[6:9], v181, v177, v[6:9]
	v_mfma_f32_16x16x4_f32 v[6:9], v182, v178, v[6:9]
	v_mfma_f32_16x16x4_f32 v[6:9], v183, v179, v[6:9]
	s_waitcnt vmcnt(0)
; __device__ __forceinline__ void phase_router(const Params& p, int l, const float* xlat, const float* xctx, int nrows) {
;     ...
;       const float4 a = *(const float4*)(xr + s * 16);
;       const float b0 = wp[s * 256], b1 = wp[s * 256 + 16], b2 = wp[s * 256 + 32], b3 = wp[s * 256 + 48];
;       ss += a.x * a.x + a.y * a.y + a.z * a.z + a.w * a.w;
;       acc = __builtin_amdgcn_mfma_f32_16x16x4f32(a.x, b0, acc, 0, 0, 0);
;       acc = __builtin_amdgcn_mfma_f32_16x16x4f32(a.y, b1, acc, 0, 0, 0);
;       acc = __builtin_amdgcn_mfma_f32_16x16x4f32(a.z, b2, acc, 0, 0, 0);
;       acc = __builtin_amdgcn_mfma_f32_16x16x4f32(a.w, b3, acc, 0, 0, 0);
;     }
;     ss += __shfl_xor(ss, 16);
;     ss += __shfl_xor(ss, 32);
;     const float rstd = rsqrtf(ss * (1.f / 1024.f) + 1e-6f);
;     const float ce = p.CE[(l * 3 + cond) * 16 + l16];
; #pragma unroll
;     for (int j = 0; j < 4; ++j) {
;       const int tk = quad * 4 + j;
;       const float r = __shfl(rstd, tk);
;       const float lg = acc[j] * r + ce;
;       float mx = lg;
; #pragma unroll
;       for (int o = 8; o; o >>= 1) mx = fmaxf(mx, __shfl_xor(mx, o));
;       const float ex = __expf(lg - mx);
;       float sm = ex;
; #pragma unroll
;       for (int o = 8; o; o >>= 1) sm += __shfl_xor(sm, o);
;       const float aff = ex / sm;
;       const int row = row0 + tk;
;       if (row < T_LAT) p.AFFT[(size_t)((row >> 13) * 16 + l16) * SEQ + (row & (SEQ - 1))] = aff;
	v_mfma_f32_16x16x4_f32 v[6:9], v42, v38, v[6:9]
	v_mul_f32_e64 v34, v42, v42
	v_mul_f32_e64 v35, v43, v43
	v_mul_f32_e64 v36, v44, v44
	v_mul_f32_e64 v37, v45, v45
	v_add_f32_e32 v34, v34, v35
	v_add_f32_e32 v34, v34, v36
	v_add_f32_e32 v34, v34, v37
	v_add_f32_e32 v0, v0, v34
	v_mfma_f32_16x16x4_f32 v[6:9], v43, v39, v[6:9]
	v_mfma_f32_16x16x4_f32 v[6:9], v44, v40, v[6:9]
	v_mfma_f32_16x16x4_f32 v[6:9], v45, v41, v[6:9]
	v_mfma_f32_16x16x4_f32 v[6:9], v58, v54, v[6:9]
	v_mul_f32_e64 v34, v58, v58
	v_mul_f32_e64 v35, v59, v59
	v_mul_f32_e64 v36, v60, v60
	v_mul_f32_e64 v37, v61, v61
	v_add_f32_e32 v34, v34, v35
	v_add_f32_e32 v34, v34, v36
	v_add_f32_e32 v34, v34, v37
	v_add_f32_e32 v0, v0, v34
	v_mfma_f32_16x16x4_f32 v[6:9], v59, v55, v[6:9]
	v_mfma_f32_16x16x4_f32 v[6:9], v60, v56, v[6:9]
	v_mfma_f32_16x16x4_f32 v[6:9], v61, v57, v[6:9]
	v_mfma_f32_16x16x4_f32 v[6:9], v66, v62, v[6:9]
	v_mul_f32_e64 v34, v66, v66
	v_mul_f32_e64 v35, v67, v67
	v_mul_f32_e64 v36, v68, v68
	v_mul_f32_e64 v37, v69, v69
	v_add_f32_e32 v34, v34, v35
	v_add_f32_e32 v34, v34, v36
	v_add_f32_e32 v34, v34, v37
	v_add_f32_e32 v0, v0, v34
	v_mfma_f32_16x16x4_f32 v[6:9], v67, v63, v[6:9]
	v_mfma_f32_16x16x4_f32 v[6:9], v68, v64, v[6:9]
	v_mfma_f32_16x16x4_f32 v[6:9], v69, v65, v[6:9]
	v_mfma_f32_16x16x4_f32 v[6:9], v74, v70, v[6:9]
	v_mul_f32_e64 v34, v74, v74
	v_mul_f32_e64 v35, v75, v75
	v_mul_f32_e64 v36, v76, v76
	v_mul_f32_e64 v37, v77, v77
	v_add_f32_e32 v34, v34, v35
	v_add_f32_e32 v34, v34, v36
	v_add_f32_e32 v34, v34, v37
	v_add_f32_e32 v0, v0, v34
	v_mfma_f32_16x16x4_f32 v[6:9], v75, v71, v[6:9]
	v_mfma_f32_16x16x4_f32 v[6:9], v76, v72, v[6:9]
	v_mfma_f32_16x16x4_f32 v[6:9], v77, v73, v[6:9]
	ds_bpermute_b32 v13, v230, v0
	v_lshl_or_b32 v12, v12, 4, v20
	s_mov_b32 s0, 0xfffff0
	v_mov_b32_e32 v14, 0x40000
	s_waitcnt lgkmcnt(0)
	v_add_f32_e32 v0, v0, v13
	ds_bpermute_b32 v13, v229, v0
	s_waitcnt lgkmcnt(0)
	v_add_f32_e32 v0, v0, v13
	v_fmamk_f32 v0, v0, 0x3a800000, v224
	v_cmp_gt_f32_e32 vcc, s85, v0
	v_mul_f32_e32 v13, 0x4b800000, v0
	s_nop 0
	v_cndmask_b32_e32 v0, v0, v13, vcc
	v_rsq_f32_e32 v0, v0
	s_nop 0
	v_mul_f32_e32 v13, 0x45800000, v0
	v_cndmask_b32_e32 v18, v0, v13, vcc
	v_ashrrev_i32_e32 v13, 31, v12
	v_lshl_add_u64 v[12:13], v[12:13], 2, v[4:5]
	global_load_dword v17, v[12:13], off
	v_add_u32_e32 v0, 0xffffc000, v29
	v_mov_b64_e32 v[12:13], s[38:39]
	v_lshrrev_b32_e32 v0, 4, v0
	global_load_dwordx2 v[12:13], v[12:13], off offset:376
	v_and_or_b32 v0, v0, s0, v20
	v_lshl_add_u32 v16, v0, 8, v14
	v_ashrrev_i32_e32 v0, 5, v11
	v_and_or_b32 v14, v0, -16, v20
	ds_bpermute_b32 v0, v22, v18
	v_ashrrev_i32_e32 v15, 31, v14
	v_lshlrev_b64 v[14:15], 15, v[14:15]
	s_waitcnt vmcnt(0) lgkmcnt(0)
	v_fma_f32 v0, v6, v0, v17
	ds_bpermute_b32 v6, v231, v0
	v_lshl_add_u64 v[14:15], v[12:13], 0, v[14:15]
	s_waitcnt lgkmcnt(0)
	v_max_f32_e32 v6, v6, v6
	v_max_f32_e32 v6, v0, v6
	ds_bpermute_b32 v19, v232, v6
	s_waitcnt lgkmcnt(0)
	v_max_f32_e32 v19, v19, v19
	v_max_f32_e32 v6, v6, v19
	ds_bpermute_b32 v19, v233, v6
	s_waitcnt lgkmcnt(0)
	v_max_f32_e32 v19, v19, v19
	v_max_f32_e32 v6, v6, v19
	ds_bpermute_b32 v19, v234, v6
	s_waitcnt lgkmcnt(0)
	v_max_f32_e32 v19, v19, v19
	v_max_f32_e32 v6, v6, v19
	v_sub_f32_e32 v0, v0, v6
	v_mul_f32_e32 v0, 0x3fb8aa3b, v0
	v_exp_f32_e32 v0, v0
	ds_bpermute_b32 v6, v231, v0
	s_waitcnt lgkmcnt(0)
	v_add_f32_e32 v6, v0, v6
	ds_bpermute_b32 v19, v232, v6
	s_waitcnt lgkmcnt(0)
	v_add_f32_e32 v6, v6, v19
	ds_bpermute_b32 v19, v233, v6
	s_waitcnt lgkmcnt(0)
	v_add_f32_e32 v6, v6, v19
	ds_bpermute_b32 v19, v234, v6
	s_waitcnt lgkmcnt(0)
	v_add_f32_e32 v6, v6, v19
	v_div_scale_f32 v19, s[0:1], v6, v6, v0
	v_rcp_f32_e32 v30, v19
	s_movk_i32 s0, 0xfc
	v_fma_f32 v31, -v19, v30, 1.0
	v_fmac_f32_e32 v30, v31, v30
	v_div_scale_f32 v31, vcc, v0, v6, v0
	v_mul_f32_e32 v32, v31, v30
	v_fma_f32 v33, -v19, v32, v31
	v_fmac_f32_e32 v32, v33, v30
	v_fma_f32 v19, -v19, v32, v31
	v_div_fmas_f32 v19, v19, v30, v32
	v_div_fixup_f32 v6, v19, v6, v0
	v_or_b32_e32 v0, v29, v10
	v_cmp_gt_i32_e32 vcc, s69, v0
	v_and_or_b32 v0, v0, s0, v16
	s_movk_i32 s0, 0x1ffc
	v_bitop3_b32 v19, v29, s0, v10 bitop3:0xc8
	v_cndmask_b32_e32 v0, v0, v19, vcc
	v_cndmask_b32_e32 v31, v13, v15, vcc
	v_cndmask_b32_e32 v30, v12, v14, vcc
	v_lshl_add_u64 v[30:31], v[0:1], 2, v[30:31]
	ds_bpermute_b32 v0, v24, v18
	global_store_dword v[30:31], v6, off
	s_waitcnt lgkmcnt(0)
	v_fma_f32 v0, v7, v0, v17
	ds_bpermute_b32 v6, v231, v0
	s_waitcnt lgkmcnt(0)
	v_max_f32_e32 v6, v6, v6
	v_max_f32_e32 v6, v0, v6
	ds_bpermute_b32 v7, v232, v6
	s_waitcnt lgkmcnt(0)
	v_max_f32_e32 v7, v7, v7
	v_max_f32_e32 v6, v6, v7
	ds_bpermute_b32 v7, v233, v6
	s_waitcnt lgkmcnt(0)
; __device__ __forceinline__ void phase_router(const Params& p, int l, const float* xlat, const float* xctx, int nrows) {
;     ...
; #pragma unroll
;     for (int j = 0; j < 4; ++j) {
;       const int tk = quad * 4 + j;
;       const float r = __shfl(rstd, tk);
;       const float lg = acc[j] * r + ce;
;       float mx = lg;
; #pragma unroll
;       for (int o = 8; o; o >>= 1) mx = fmaxf(mx, __shfl_xor(mx, o));
;       const float ex = __expf(lg - mx);
;       float sm = ex;
; #pragma unroll
;       for (int o = 8; o; o >>= 1) sm += __shfl_xor(sm, o);
;       const float aff = ex / sm;
;       const int row = row0 + tk;
;       if (row < T_LAT) p.AFFT[(size_t)((row >> 13) * 16 + l16) * SEQ + (row & (SEQ - 1))] = aff;
;       else { const int rc = row - T_LAT; p.AFFT[(size_t)32 * SEQ + ((rc >> 8) * 16 + l16) * CTX + (rc & 255)] = aff; }
;     }
	v_max_f32_e32 v7, v7, v7
	v_max_f32_e32 v6, v6, v7
	ds_bpermute_b32 v7, v234, v6
	s_waitcnt lgkmcnt(0)
	v_max_f32_e32 v7, v7, v7
	v_max_f32_e32 v6, v6, v7
	v_sub_f32_e32 v0, v0, v6
	v_mul_f32_e32 v0, 0x3fb8aa3b, v0
	v_exp_f32_e32 v0, v0
	ds_bpermute_b32 v6, v231, v0
	s_waitcnt lgkmcnt(0)
	v_add_f32_e32 v6, v0, v6
	ds_bpermute_b32 v7, v232, v6
	s_waitcnt lgkmcnt(0)
	v_add_f32_e32 v6, v6, v7
	ds_bpermute_b32 v7, v233, v6
	s_waitcnt lgkmcnt(0)
	v_add_f32_e32 v6, v6, v7
	ds_bpermute_b32 v7, v234, v6
	s_waitcnt lgkmcnt(0)
	v_add_f32_e32 v6, v6, v7
	v_div_scale_f32 v7, s[0:1], v6, v6, v0
	v_rcp_f32_e32 v19, v7
	s_movk_i32 s0, 0x1ffd
	v_fma_f32 v30, -v7, v19, 1.0
	v_fmac_f32_e32 v19, v30, v19
	v_div_scale_f32 v30, vcc, v0, v6, v0
	v_mul_f32_e32 v31, v30, v19
	v_fma_f32 v32, -v7, v31, v30
	v_fmac_f32_e32 v31, v32, v19
	v_fma_f32 v7, -v7, v31, v30
	v_div_fmas_f32 v7, v7, v19, v31
	v_div_fixup_f32 v19, v7, v6, v0
	v_or_b32_e32 v0, v29, v23
	v_bitop3_b32 v6, v29, s0, v23 bitop3:0xc8
	s_movk_i32 s0, 0xfd
	v_cmp_gt_i32_e32 vcc, s69, v0
	v_and_or_b32 v0, v0, s0, v16
	s_nop 0
	v_cndmask_b32_e32 v0, v0, v6, vcc
	v_cndmask_b32_e32 v7, v13, v15, vcc
	v_cndmask_b32_e32 v6, v12, v14, vcc
	v_lshl_add_u64 v[6:7], v[0:1], 2, v[6:7]
	ds_bpermute_b32 v0, v26, v18
	global_store_dword v[6:7], v19, off
	s_waitcnt lgkmcnt(0)
	v_fma_f32 v0, v8, v0, v17
	ds_bpermute_b32 v6, v231, v0
	s_waitcnt lgkmcnt(0)
	v_max_f32_e32 v6, v6, v6
	v_max_f32_e32 v6, v0, v6
	ds_bpermute_b32 v7, v232, v6
	s_waitcnt lgkmcnt(0)
	v_max_f32_e32 v7, v7, v7
	v_max_f32_e32 v6, v6, v7
	ds_bpermute_b32 v7, v233, v6
	s_waitcnt lgkmcnt(0)
	v_max_f32_e32 v7, v7, v7
	v_max_f32_e32 v6, v6, v7
	ds_bpermute_b32 v7, v234, v6
	s_waitcnt lgkmcnt(0)
	v_max_f32_e32 v7, v7, v7
	v_max_f32_e32 v6, v6, v7
	v_sub_f32_e32 v0, v0, v6
	v_mul_f32_e32 v0, 0x3fb8aa3b, v0
	v_exp_f32_e32 v0, v0
	ds_bpermute_b32 v6, v231, v0
	s_waitcnt lgkmcnt(0)
	v_add_f32_e32 v6, v0, v6
	ds_bpermute_b32 v7, v232, v6
	s_waitcnt lgkmcnt(0)
	v_add_f32_e32 v6, v6, v7
	ds_bpermute_b32 v7, v233, v6
	s_waitcnt lgkmcnt(0)
	v_add_f32_e32 v6, v6, v7
	ds_bpermute_b32 v7, v234, v6
	s_waitcnt lgkmcnt(0)
	v_add_f32_e32 v6, v6, v7
	v_div_scale_f32 v7, s[0:1], v6, v6, v0
	v_rcp_f32_e32 v8, v7
	s_movk_i32 s0, 0x1ffe
	v_fma_f32 v19, -v7, v8, 1.0
	v_fmac_f32_e32 v8, v19, v8
	v_div_scale_f32 v19, vcc, v0, v6, v0
	v_mul_f32_e32 v30, v19, v8
	v_fma_f32 v31, -v7, v30, v19
	v_fmac_f32_e32 v30, v31, v8
	v_fma_f32 v7, -v7, v30, v19
	v_div_fmas_f32 v7, v7, v8, v30
	v_div_fixup_f32 v8, v7, v6, v0
	v_or_b32_e32 v0, v29, v25
	v_bitop3_b32 v6, v29, s0, v25 bitop3:0xc8
	s_movk_i32 s0, 0xfe
	v_cmp_gt_i32_e32 vcc, s69, v0
	v_and_or_b32 v0, v0, s0, v16
	s_nop 0
	v_cndmask_b32_e32 v0, v0, v6, vcc
	v_cndmask_b32_e32 v7, v13, v15, vcc
	v_cndmask_b32_e32 v6, v12, v14, vcc
	v_lshl_add_u64 v[6:7], v[0:1], 2, v[6:7]
	ds_bpermute_b32 v0, v28, v18
	global_store_dword v[6:7], v8, off
	s_waitcnt lgkmcnt(0)
	v_fmac_f32_e32 v17, v9, v0
	ds_bpermute_b32 v0, v231, v17
	s_waitcnt lgkmcnt(0)
	v_max_f32_e32 v0, v0, v0
	v_max_f32_e32 v0, v17, v0
	ds_bpermute_b32 v6, v232, v0
	s_waitcnt lgkmcnt(0)
	v_max_f32_e32 v6, v6, v6
	v_max_f32_e32 v0, v0, v6
	ds_bpermute_b32 v6, v233, v0
	s_waitcnt lgkmcnt(0)
	v_max_f32_e32 v6, v6, v6
	v_max_f32_e32 v0, v0, v6
	ds_bpermute_b32 v6, v234, v0
	s_waitcnt lgkmcnt(0)
	v_max_f32_e32 v6, v6, v6
	v_max_f32_e32 v0, v0, v6
	v_sub_f32_e32 v0, v17, v0
	v_mul_f32_e32 v0, 0x3fb8aa3b, v0
	v_exp_f32_e32 v0, v0
	ds_bpermute_b32 v6, v231, v0
	s_waitcnt lgkmcnt(0)
	v_add_f32_e32 v6, v0, v6
	ds_bpermute_b32 v7, v232, v6
	s_waitcnt lgkmcnt(0)
	v_add_f32_e32 v6, v6, v7
	ds_bpermute_b32 v7, v233, v6
	s_waitcnt lgkmcnt(0)
	v_add_f32_e32 v6, v6, v7
	ds_bpermute_b32 v7, v234, v6
	s_waitcnt lgkmcnt(0)
	v_add_f32_e32 v6, v6, v7
	v_div_scale_f32 v7, s[0:1], v6, v6, v0
	v_rcp_f32_e32 v8, v7
	s_movk_i32 s0, 0x1fff
	v_fma_f32 v9, -v7, v8, 1.0
	v_fmac_f32_e32 v8, v9, v8
	v_div_scale_f32 v9, vcc, v0, v6, v0
	v_mul_f32_e32 v17, v9, v8
	v_fma_f32 v18, -v7, v17, v9
	v_fmac_f32_e32 v17, v18, v8
	v_fma_f32 v7, -v7, v17, v9
	v_div_fmas_f32 v7, v7, v8, v17
	v_div_fixup_f32 v8, v7, v6, v0
	v_or_b32_e32 v0, v29, v27
	v_bitop3_b32 v6, v29, s0, v27 bitop3:0xc8
	s_movk_i32 s0, 0xff
	v_cmp_gt_i32_e32 vcc, s69, v0
	v_and_or_b32 v0, v0, s0, v16
	v_readlane_b32 s0, v254, 47
	v_cndmask_b32_e32 v0, v0, v6, vcc
	v_cndmask_b32_e32 v7, v13, v15, vcc
	v_add_u32_e32 v11, s0, v11
	v_cndmask_b32_e32 v6, v12, v14, vcc
	v_cmp_le_i32_e32 vcc, s8, v11
	v_lshl_add_u64 v[6:7], v[0:1], 2, v[6:7]
	s_or_b64 s[42:43], vcc, s[42:43]
	global_store_dword v[6:7], v8, off
	v_readlane_b32 s1, v254, 48
	s_andn2_b64 exec, exec, s[42:43]
	s_cbranch_execnz .LBB0_911
